# pair-scoped P1->P2 barrier + 24 us per-pair start stagger (offsets 0/24/48/72 us; the split-phase P3/P6/conversion guards bound the skew)
# baseline (speedup 1.0000x reference)
; #define LAS __attribute__((address_space(3)))
; __global__ void __launch_bounds__(NWAVES * 64, 2) mk_fwd(Args a) {
;     ...
;     for (int l = 0; l < NLAYER; ++l) {
;         unsigned char* wl = ws + WS_W + (size_t)l * W_LAYER;
; #pragma unroll 1
;         for (int rep1 = 0; rep1 < REP_P1; ++rep1) {
;             pg8::Gemm g{XB, (const bf16u*)(wl + WL_IN), NTOK, INW, DMOD}; int bxp = bx; asm volatile("" : "+s"(bxp)); pg8::StaticOrder S; S.init(NTOK, INW, G, bxp);
;             pg8::Unit u0; int pm0 = -1; if (S.next(0, u0)) pm0 = u0.pm;
;             { int tt_ = threadIdx.x; asm volatile("" : "+v"(tt_)); if (pm0 >= 0 && tt_ < 256) ((LAS float*)(L + RING_BYTES))[tt_] = pg8::row_rstd(ssqA, pm0 * 256 + tt_); }
;             __syncthreads();
;             pg8::EpiProj E{Qb, BUFE, ssqA, rope, attn_body::C2, pm0, (const LAS float*)(L + RING_BYTES)};
;             pg8::gemm_phase<pg8::EpiProj, pg8::StaticOrder, true, true>(L, g, S, E);
;     ...
;                 const int nwg5 = (NTOK / 256) * (2 * DFF / 256), rem = nwg5 % G;
;                 const bool light = (rem == 0) || (bxp >= rem);
;                 if (light) { int tc_ = threadIdx.x; asm volatile("" : "+v"(tc_)); const int lnc = tc_ & 63; const int nl = (rem == 0) ? G : G - rem, li = (rem == 0) ? bxp : bxp - rem;
.LBB0_135:
	v_writelane_b32 v255, s72, 2
	s_nop 1
	v_writelane_b32 v255, s73, 3
	s_or_b64 exec, exec, s[2:3]
	s_add_u32 s0, s42, 0x100000
	s_addc_u32 s1, s43, 0
	v_writelane_b32 v255, s0, 4
	v_readlane_b32 s4, v253, 38
	s_mov_b32 s91, 0
	v_writelane_b32 v255, s1, 5
	s_add_u32 s0, s42, 0x200000
	s_addc_u32 s1, s43, 0
	s_add_u32 s82, s42, 0x9e00000
	s_addc_u32 s83, s43, 0
	s_add_u32 s6, s42, 0xbe00000
	v_writelane_b32 v255, s0, 6
	s_addc_u32 s7, s43, 0
	v_mov_b32_e32 v245, 0x358637bd
	v_writelane_b32 v255, s1, 7
	s_add_u32 s0, s42, 0xde00000
	v_writelane_b32 v255, s0, 8
	s_addc_u32 s0, s43, 0
	v_writelane_b32 v255, s0, 9
	s_add_u32 s0, s42, 0xfe00000
	v_writelane_b32 v255, s0, 10
	s_addc_u32 s0, s43, 0
	s_add_u32 s28, s42, 0x11e00000
	s_addc_u32 s29, s43, 0
	s_add_u32 s30, s42, 0x13e00000
	s_addc_u32 s31, s43, 0
	v_writelane_b32 v255, s0, 11
	s_add_u32 s0, s42, 0x17e00000
	s_addc_u32 s1, s43, 0
	v_writelane_b32 v255, s0, 12
	s_movk_i32 s61, 0x2000
	v_mov_b32_e32 v1, 0
	v_writelane_b32 v255, s1, 13
	s_add_u32 s0, s42, 0x19e00000
	s_addc_u32 s1, s43, 0
	s_add_u32 s14, s42, 0x1be00000
	s_addc_u32 s15, s43, 0
	s_add_u32 s86, s42, 0x1de00000
	s_addc_u32 s87, s43, 0
	s_ashr_i32 s79, s80, 31
	v_writelane_b32 v255, s0, 14
	s_cmpk_eq_i32 s80, 0x100
	s_mov_b32 s88, 0x8000
	v_writelane_b32 v255, s1, 15
	s_cselect_b64 s[0:1], -1, 0
	v_writelane_b32 v255, s0, 16
	s_lshl_b32 s89, s80, 2
	s_mov_b32 s27, 0xa000
	v_writelane_b32 v255, s1, 17
	s_abs_i32 s0, s80
	s_waitcnt lgkmcnt(0)
	v_cvt_f32_u32_e32 v0, s0
	s_lshl_b32 s1, s4, 5
	v_writelane_b32 v255, s1, 18
	s_sub_i32 s1, 0, s0
	v_rcp_iflag_f32_e32 v0, v0
	s_mov_b32 s26, 0xc000
	v_mov_b32_e32 v234, 1
	s_movk_i32 s10, 0x3ff
	v_mul_f32_e32 v0, 0x4f7ffffe, v0
	v_cvt_u32_f32_e32 v0, v0
	v_mov_b64_e32 v[236:237], 0x800
	v_mov_b32_e32 v235, 0x3e38aa3b
	v_mov_b32_e32 v248, 0xff800000
	v_readfirstlane_b32 s2, v0
	s_mul_i32 s1, s1, s2
	s_mul_hi_u32 s1, s2, s1
	s_add_i32 s2, s2, s1
	s_mul_hi_u32 s1, s2, 0x580
	s_mul_i32 s1, s1, s0
	s_sub_i32 s1, 0x580, s1
	s_sub_i32 s2, s1, s0
	s_cmp_ge_u32 s1, s0
	s_cselect_b32 s1, s2, s1
	s_sub_i32 s2, s1, s0
	s_cmp_ge_u32 s1, s0
	s_cselect_b32 s5, s2, s1
	s_cmp_eq_u32 s5, 0
	s_cselect_b64 s[2:3], -1, 0
	s_sub_i32 s0, s80, s5
	s_lshl_b32 s0, s0, 3
	v_writelane_b32 v255, s0, 19
	s_lshl_b32 s0, s80, 4
	v_writelane_b32 v255, s0, 20
	s_lshl_b32 s0, s4, 6
	s_lshl_b32 s1, s5, 9
	s_sub_i32 s8, s0, s1
	s_sub_i32 s0, s34, s1
	v_writelane_b32 v255, s0, 21
	s_lshl_b32 s0, s4, 2
	s_lshl_b32 s1, s5, 5
	s_sub_i32 s0, s0, s1
	v_writelane_b32 v255, s0, 22
	s_lshl_b32 s0, s80, 5
	s_sub_i32 s0, s0, s1
	v_writelane_b32 v255, s0, 23
	s_lshl_b32 s0, s4, 7
	s_lshl_b32 s1, s5, 10
	s_sub_i32 s0, s0, s1
	s_add_i32 s0, s0, 0xfff92000
	v_writelane_b32 v255, s0, 24
	s_lshl_b32 s0, s80, 10
	s_sub_i32 s0, s0, s1
	v_writelane_b32 v255, s0, 25
	s_lshl_b32 s0, s5, 3
	s_sub_i32 s1, s4, s0
	s_add_i32 s4, s1, 0xfffff240
	v_writelane_b32 v255, s4, 26
	s_mov_b32 s4, s74
	v_writelane_b32 v255, s4, 27
	s_sub_i32 s0, s74, s0
	s_xor_b64 s[2:3], s[2:3], -1
	v_writelane_b32 v255, s5, 28
	v_writelane_b32 v255, s0, 29
	s_add_i32 s0, s8, 0xfffc9000
	v_writelane_b32 v255, s0, 30
	s_add_i32 s0, s1, 0xfffff500
	v_writelane_b32 v255, s0, 31
	s_add_i32 s0, s1, 0xf500
	v_writelane_b32 v255, s0, 32
	v_writelane_b32 v255, s8, 33
	s_add_i32 s0, s8, 0xfffd4000
	v_writelane_b32 v255, s0, 34
	s_lshl_b32 s0, s80, 12
	s_lshl_b32 s1, s5, 12
	v_writelane_b32 v255, s5, 35
	s_sub_i32 s0, s0, s1
	v_writelane_b32 v255, s0, 36
	s_add_i32 s1, 0, 0x23fc0
	v_writelane_b32 v255, s1, 37
	s_add_i32 s1, 0, 0x23fc4
	v_writelane_b32 v255, s1, 38
	v_writelane_b32 v255, s2, 39
	s_lshl_b32 s44, s80, 6
	s_mov_b32 s5, 0x18000
	v_writelane_b32 v255, s3, 40
	v_writelane_b32 v255, s78, 41
	v_writelane_b32 v255, s82, 42
	s_mov_b32 s0, 0x50000
	v_mov_b64_e32 v[230:231], 0xff
	v_writelane_b32 v255, s83, 43
	s_mov_b32 s11, 0x41000000
	s_mov_b64 s[8:9], 0x40000
	s_mov_b64 s[70:71], 0x80
	s_mov_b64 s[62:63], 0x2000
	s_mov_b64 s[94:95], 0x20000
	s_mov_b64 s[72:73], 0x60000
	s_mov_b64 s[74:75], 0x80000
	s_mov_b64 s[66:67], 0xfe40000
	s_mov_b64 s[84:85], 0xfe40080
	s_mov_b32 s92, s91
	v_writelane_b32 v255, s79, 44
	s_barrier
	s_mov_b32 s98, 0
	s_mov_b32 s99, 0
	s_mov_b32 s100, 0
	s_cmpk_lg_i32 s80, 0x100
	s_cbranch_scc1 .Lgb_setup_done
	s_add_u32 s12, s42, 0x318000
	s_addc_u32 s13, s43, 0
	v_and_b32_e32 v2, 63, v244
	v_lshlrev_b32_e32 v3, 4, v2
	global_load_dwordx4 v[4:7], v3, s[12:13] sc1
	v_and_b32_e32 v8, 1, v2
	s_waitcnt vmcnt(0)
	v_readlane_b32 s1, v4, 0
	v_readlane_b32 s2, v5, 0
	v_readlane_b32 s3, v6, 0
	v_readlane_b32 s4, v7, 0
	v_readlane_b32 s16, v4, 1
	v_readlane_b32 s17, v5, 1
	v_readlane_b32 s18, v6, 1
	v_readlane_b32 s19, v7, 1
	v_cmp_eq_u32_e32 vcc, 1, v8
	s_nop 3
	v_mov_b32_e32 v9, s1
	v_mov_b32_e32 v10, s16
	v_cndmask_b32_e32 v9, v9, v10, vcc
	v_mov_b32_e32 v11, s2
	v_mov_b32_e32 v10, s17
	v_cndmask_b32_e32 v11, v11, v10, vcc
	v_mov_b32_e32 v12, s3
	v_mov_b32_e32 v10, s18
	v_cndmask_b32_e32 v12, v12, v10, vcc
	v_mov_b32_e32 v13, s4
	v_mov_b32_e32 v10, s19
	v_cndmask_b32_e32 v13, v13, v10, vcc
	v_xor_b32_e32 v9, v9, v4
	v_xor_b32_e32 v11, v11, v5
	v_xor_b32_e32 v12, v12, v6
	v_xor_b32_e32 v13, v13, v7
	v_or3_b32 v9, v9, v11, v12
	v_or_b32_e32 v9, v9, v13
	v_min_u32_e32 v10, v4, v5
	v_min3_u32 v10, v10, v6, v7
	v_cmp_ne_u32_e32 vcc, 0, v9
	v_cmp_eq_u32_e64 s[2:3], 0, v10
	s_nop 1
	s_or_b64 s[2:3], s[2:3], vcc
	s_cmp_lg_u64 s[2:3], 0
	s_cbranch_scc1 .Lgb_setup_done
	s_mov_b32 s98, 1
	v_readlane_b32 s4, v253, 1
	s_nop 3
	s_bfe_u32 s4, s4, 0x20001
	s_mul_i32 s4, s4, 6
	s_cmp_eq_u32 s4, 0
	s_cbranch_scc1 .Lgb_setup_done
